# sample attention score loop: per-lane K mapping changed so each load instruction reads one contiguous 64-byte sector per key row (same dot products, permuted k order)
# baseline (speedup 1.0000x reference)
.LBB0_849:
	s_ashr_i32 s59, s58, 31
	s_lshl_b64 s[40:41], s[58:59], 19
	s_or_b64 s[40:41], s[40:41], s[48:49]
	s_lshl_b64 s[62:63], s[40:41], 2
	s_waitcnt lgkmcnt(0)
	s_add_u32 s40, s64, s62
	s_addc_u32 s41, s65, s63
	s_add_i32 s58, s67, 0x2000
	s_ashr_i32 s59, s58, 31
	v_lshl_add_u64 v[0:1], s[40:41], 0, v[66:67]
	s_and_b32 s40, s66, 3
	s_lshl_b64 s[64:65], s[58:59], 12
	s_lshl_b32 s40, s40, 10
	s_or_b32 s64, s64, s40
	v_mov_b32_e32 v4, 0
	v_lshl_add_u64 v[28:29], v[0:1], 0, v[64:65]
	v_lshl_add_u64 v[30:31], v[70:71], 0, s[64:65]
	s_mov_b64 s[64:65], 0
	v_mov_b32_e32 v34, v90
	v_mov_b32_e32 v5, v4
	v_mov_b32_e32 v6, v4
	v_mov_b32_e32 v7, v4
	v_mov_b32_e32 v0, v4
	v_mov_b32_e32 v1, v4
	v_mov_b32_e32 v2, v4
	v_mov_b32_e32 v3, v4
	s_and_b64 vcc, exec, s[14:15]
	s_cbranch_vccnz .LBB0_851
	s_mov_b64 s[40:41], 0x20000
	v_and_b32_e32 v160, 0x30, v164
	v_sub_co_u32_e32 v224, vcc, v28, v160
	s_nop 1
	v_subbrev_co_u32_e32 v225, vcc, 0, v29, vcc
	v_lshl_add_u64 v[222:223], v[224:225], 0, s[40:41]
	v_lshrrev_b32_e32 v160, 1, v160
	v_sub_u32_e32 v161, v34, v160
	global_load_dwordx4 v[122:125], v[224:225], off
	global_load_dwordx4 v[126:129], v[224:225], off offset:64
	global_load_dwordx4 v[130:133], v[222:223], off
	global_load_dwordx4 v[134:137], v[222:223], off offset:64
	global_load_dwordx4 v[138:141], v[224:225], off offset:128
	global_load_dwordx4 v[142:145], v[224:225], off offset:192
	global_load_dwordx4 v[146:149], v[222:223], off offset:128
	global_load_dwordx4 v[150:153], v[222:223], off offset:192
	global_load_dwordx4 v[166:169], v[224:225], off offset:256
	global_load_dwordx4 v[170:173], v[224:225], off offset:320
	global_load_dwordx4 v[174:177], v[222:223], off offset:256
	global_load_dwordx4 v[178:181], v[222:223], off offset:320
	global_load_dwordx4 v[198:201], v[224:225], off offset:384
	global_load_dwordx4 v[202:205], v[224:225], off offset:448
	global_load_dwordx4 v[206:209], v[222:223], off offset:384
	global_load_dwordx4 v[210:213], v[222:223], off offset:448
	ds_read_b64 v[214:215], v161
	ds_read_b64 v[216:217], v161 offset:32
	ds_read_b64 v[218:219], v161 offset:64
	ds_read_b64 v[220:221], v161 offset:96
	s_waitcnt vmcnt(12)
	s_waitcnt lgkmcnt(2)
	v_cndmask_b32_e64 v214, v214, 0, s[8:9]
	v_cndmask_b32_e64 v215, v215, 0, s[8:9]
	v_cndmask_b32_e64 v216, v216, 0, s[8:9]
	v_cndmask_b32_e64 v217, v217, 0, s[8:9]
	v_cvt_pk_bf16_f32 v122, v122, v123
	v_cvt_pk_bf16_f32 v123, v124, v125
	v_cvt_pk_bf16_f32 v124, v126, v127
	v_cvt_pk_bf16_f32 v125, v128, v129
	v_cvt_pk_bf16_f32 v130, v130, v131
	v_cvt_pk_bf16_f32 v131, v132, v133
	v_cvt_pk_bf16_f32 v132, v134, v135
	v_cvt_pk_bf16_f32 v133, v136, v137
	v_mfma_f32_16x16x32_bf16 v[4:7], v[122:125], v[214:217], v[4:7]
	s_nop 0
	v_mfma_f32_16x16x32_bf16 v[0:3], v[130:133], v[214:217], v[0:3]
	global_load_dwordx4 v[122:125], v[224:225], off offset:512
	global_load_dwordx4 v[126:129], v[224:225], off offset:576
	global_load_dwordx4 v[130:133], v[222:223], off offset:512
	global_load_dwordx4 v[134:137], v[222:223], off offset:576
	ds_read_b64 v[214:215], v161 offset:128
	ds_read_b64 v[216:217], v161 offset:160
	s_waitcnt vmcnt(12)
	s_waitcnt lgkmcnt(2)
	v_cndmask_b32_e64 v218, v218, 0, s[8:9]
	v_cndmask_b32_e64 v219, v219, 0, s[8:9]
	v_cndmask_b32_e64 v220, v220, 0, s[8:9]
	v_cndmask_b32_e64 v221, v221, 0, s[8:9]
	v_cvt_pk_bf16_f32 v138, v138, v139
	v_cvt_pk_bf16_f32 v139, v140, v141
	v_cvt_pk_bf16_f32 v140, v142, v143
	v_cvt_pk_bf16_f32 v141, v144, v145
	v_cvt_pk_bf16_f32 v146, v146, v147
	v_cvt_pk_bf16_f32 v147, v148, v149
	v_cvt_pk_bf16_f32 v148, v150, v151
	v_cvt_pk_bf16_f32 v149, v152, v153
	v_mfma_f32_16x16x32_bf16 v[4:7], v[138:141], v[218:221], v[4:7]
	s_nop 0
	v_mfma_f32_16x16x32_bf16 v[0:3], v[146:149], v[218:221], v[0:3]
	global_load_dwordx4 v[138:141], v[224:225], off offset:640
	global_load_dwordx4 v[142:145], v[224:225], off offset:704
	global_load_dwordx4 v[146:149], v[222:223], off offset:640
	global_load_dwordx4 v[150:153], v[222:223], off offset:704
	ds_read_b64 v[218:219], v161 offset:192
	ds_read_b64 v[220:221], v161 offset:224
	s_waitcnt vmcnt(12)
	s_waitcnt lgkmcnt(2)
	v_cndmask_b32_e64 v214, v214, 0, s[8:9]
	v_cndmask_b32_e64 v215, v215, 0, s[8:9]
	v_cndmask_b32_e64 v216, v216, 0, s[8:9]
	v_cndmask_b32_e64 v217, v217, 0, s[8:9]
	v_cvt_pk_bf16_f32 v166, v166, v167
	v_cvt_pk_bf16_f32 v167, v168, v169
	v_cvt_pk_bf16_f32 v168, v170, v171
	v_cvt_pk_bf16_f32 v169, v172, v173
	v_cvt_pk_bf16_f32 v174, v174, v175
	v_cvt_pk_bf16_f32 v175, v176, v177
	v_cvt_pk_bf16_f32 v176, v178, v179
	v_cvt_pk_bf16_f32 v177, v180, v181
	v_mfma_f32_16x16x32_bf16 v[4:7], v[166:169], v[214:217], v[4:7]
	s_nop 0
	v_mfma_f32_16x16x32_bf16 v[0:3], v[174:177], v[214:217], v[0:3]
	global_load_dwordx4 v[166:169], v[224:225], off offset:768
	global_load_dwordx4 v[170:173], v[224:225], off offset:832
	global_load_dwordx4 v[174:177], v[222:223], off offset:768
	global_load_dwordx4 v[178:181], v[222:223], off offset:832
	ds_read_b64 v[214:215], v161 offset:256
	ds_read_b64 v[216:217], v161 offset:288
	s_waitcnt vmcnt(12)
	s_waitcnt lgkmcnt(2)
	v_cndmask_b32_e64 v218, v218, 0, s[8:9]
	v_cndmask_b32_e64 v219, v219, 0, s[8:9]
	v_cndmask_b32_e64 v220, v220, 0, s[8:9]
	v_cndmask_b32_e64 v221, v221, 0, s[8:9]
	v_cvt_pk_bf16_f32 v198, v198, v199
	v_cvt_pk_bf16_f32 v199, v200, v201
	v_cvt_pk_bf16_f32 v200, v202, v203
	v_cvt_pk_bf16_f32 v201, v204, v205
	v_cvt_pk_bf16_f32 v206, v206, v207
	v_cvt_pk_bf16_f32 v207, v208, v209
	v_cvt_pk_bf16_f32 v208, v210, v211
	v_cvt_pk_bf16_f32 v209, v212, v213
	v_mfma_f32_16x16x32_bf16 v[4:7], v[198:201], v[218:221], v[4:7]
	s_nop 0
	v_mfma_f32_16x16x32_bf16 v[0:3], v[206:209], v[218:221], v[0:3]
	global_load_dwordx4 v[198:201], v[224:225], off offset:896
	global_load_dwordx4 v[202:205], v[224:225], off offset:960
	global_load_dwordx4 v[206:209], v[222:223], off offset:896
	global_load_dwordx4 v[210:213], v[222:223], off offset:960
	ds_read_b64 v[218:219], v161 offset:320
	ds_read_b64 v[220:221], v161 offset:352
	s_waitcnt vmcnt(12)
	s_waitcnt lgkmcnt(2)
	v_cndmask_b32_e64 v214, v214, 0, s[8:9]
	v_cndmask_b32_e64 v215, v215, 0, s[8:9]
	v_cndmask_b32_e64 v216, v216, 0, s[8:9]
	v_cndmask_b32_e64 v217, v217, 0, s[8:9]
	v_cvt_pk_bf16_f32 v122, v122, v123
	v_cvt_pk_bf16_f32 v123, v124, v125
	v_cvt_pk_bf16_f32 v124, v126, v127
	v_cvt_pk_bf16_f32 v125, v128, v129
	v_cvt_pk_bf16_f32 v130, v130, v131
	v_cvt_pk_bf16_f32 v131, v132, v133
	v_cvt_pk_bf16_f32 v132, v134, v135
	v_cvt_pk_bf16_f32 v133, v136, v137
	v_mfma_f32_16x16x32_bf16 v[4:7], v[122:125], v[214:217], v[4:7]
	s_nop 0
	v_mfma_f32_16x16x32_bf16 v[0:3], v[130:133], v[214:217], v[0:3]
	global_load_dwordx4 v[122:125], v[224:225], off offset:1024
	global_load_dwordx4 v[126:129], v[224:225], off offset:1088
	global_load_dwordx4 v[130:133], v[222:223], off offset:1024
	global_load_dwordx4 v[134:137], v[222:223], off offset:1088
	ds_read_b64 v[214:215], v161 offset:384
	ds_read_b64 v[216:217], v161 offset:416
	s_waitcnt vmcnt(12)
	s_waitcnt lgkmcnt(2)
	v_cndmask_b32_e64 v218, v218, 0, s[8:9]
	v_cndmask_b32_e64 v219, v219, 0, s[8:9]
	v_cndmask_b32_e64 v220, v220, 0, s[8:9]
	v_cndmask_b32_e64 v221, v221, 0, s[8:9]
	v_cvt_pk_bf16_f32 v138, v138, v139
	v_cvt_pk_bf16_f32 v139, v140, v141
	v_cvt_pk_bf16_f32 v140, v142, v143
	v_cvt_pk_bf16_f32 v141, v144, v145
	v_cvt_pk_bf16_f32 v146, v146, v147
	v_cvt_pk_bf16_f32 v147, v148, v149
	v_cvt_pk_bf16_f32 v148, v150, v151
	v_cvt_pk_bf16_f32 v149, v152, v153
	v_mfma_f32_16x16x32_bf16 v[4:7], v[138:141], v[218:221], v[4:7]
	s_nop 0
	v_mfma_f32_16x16x32_bf16 v[0:3], v[146:149], v[218:221], v[0:3]
	global_load_dwordx4 v[138:141], v[224:225], off offset:1152
	global_load_dwordx4 v[142:145], v[224:225], off offset:1216
	global_load_dwordx4 v[146:149], v[222:223], off offset:1152
	global_load_dwordx4 v[150:153], v[222:223], off offset:1216
	ds_read_b64 v[218:219], v161 offset:448
	ds_read_b64 v[220:221], v161 offset:480
	s_waitcnt vmcnt(12)
	s_waitcnt lgkmcnt(2)
	v_cndmask_b32_e64 v214, v214, 0, s[8:9]
	v_cndmask_b32_e64 v215, v215, 0, s[8:9]
	v_cndmask_b32_e64 v216, v216, 0, s[8:9]
	v_cndmask_b32_e64 v217, v217, 0, s[8:9]
	v_cvt_pk_bf16_f32 v166, v166, v167
	v_cvt_pk_bf16_f32 v167, v168, v169
	v_cvt_pk_bf16_f32 v168, v170, v171
	v_cvt_pk_bf16_f32 v169, v172, v173
	v_cvt_pk_bf16_f32 v174, v174, v175
	v_cvt_pk_bf16_f32 v175, v176, v177
	v_cvt_pk_bf16_f32 v176, v178, v179
	v_cvt_pk_bf16_f32 v177, v180, v181
	v_mfma_f32_16x16x32_bf16 v[4:7], v[166:169], v[214:217], v[4:7]
	s_nop 0
	v_mfma_f32_16x16x32_bf16 v[0:3], v[174:177], v[214:217], v[0:3]
	global_load_dwordx4 v[166:169], v[224:225], off offset:1280
	global_load_dwordx4 v[170:173], v[224:225], off offset:1344
	global_load_dwordx4 v[174:177], v[222:223], off offset:1280
	global_load_dwordx4 v[178:181], v[222:223], off offset:1344
	ds_read_b64 v[214:215], v161 offset:512
	ds_read_b64 v[216:217], v161 offset:544
	s_waitcnt vmcnt(12)
	s_waitcnt lgkmcnt(2)
	v_cndmask_b32_e64 v218, v218, 0, s[8:9]
	v_cndmask_b32_e64 v219, v219, 0, s[8:9]
	v_cndmask_b32_e64 v220, v220, 0, s[8:9]
	v_cndmask_b32_e64 v221, v221, 0, s[8:9]
	v_cvt_pk_bf16_f32 v198, v198, v199
	v_cvt_pk_bf16_f32 v199, v200, v201
	v_cvt_pk_bf16_f32 v200, v202, v203
	v_cvt_pk_bf16_f32 v201, v204, v205
	v_cvt_pk_bf16_f32 v206, v206, v207
	v_cvt_pk_bf16_f32 v207, v208, v209
	v_cvt_pk_bf16_f32 v208, v210, v211
	v_cvt_pk_bf16_f32 v209, v212, v213
	v_mfma_f32_16x16x32_bf16 v[4:7], v[198:201], v[218:221], v[4:7]
	s_nop 0
	v_mfma_f32_16x16x32_bf16 v[0:3], v[206:209], v[218:221], v[0:3]
	global_load_dwordx4 v[198:201], v[224:225], off offset:1408
	global_load_dwordx4 v[202:205], v[224:225], off offset:1472
	global_load_dwordx4 v[206:209], v[222:223], off offset:1408
	global_load_dwordx4 v[210:213], v[222:223], off offset:1472
	ds_read_b64 v[218:219], v161 offset:576
	ds_read_b64 v[220:221], v161 offset:608
	s_waitcnt vmcnt(12)
	s_waitcnt lgkmcnt(2)
	v_cndmask_b32_e64 v214, v214, 0, s[8:9]
	v_cndmask_b32_e64 v215, v215, 0, s[8:9]
	v_cndmask_b32_e64 v216, v216, 0, s[8:9]
	v_cndmask_b32_e64 v217, v217, 0, s[8:9]
	v_cvt_pk_bf16_f32 v122, v122, v123
	v_cvt_pk_bf16_f32 v123, v124, v125
	v_cvt_pk_bf16_f32 v124, v126, v127
	v_cvt_pk_bf16_f32 v125, v128, v129
	v_cvt_pk_bf16_f32 v130, v130, v131
	v_cvt_pk_bf16_f32 v131, v132, v133
	v_cvt_pk_bf16_f32 v132, v134, v135
	v_cvt_pk_bf16_f32 v133, v136, v137
	v_mfma_f32_16x16x32_bf16 v[4:7], v[122:125], v[214:217], v[4:7]
	s_nop 0
	v_mfma_f32_16x16x32_bf16 v[0:3], v[130:133], v[214:217], v[0:3]
	global_load_dwordx4 v[122:125], v[224:225], off offset:1536
	global_load_dwordx4 v[126:129], v[224:225], off offset:1600
	global_load_dwordx4 v[130:133], v[222:223], off offset:1536
	global_load_dwordx4 v[134:137], v[222:223], off offset:1600
	ds_read_b64 v[214:215], v161 offset:640
	ds_read_b64 v[216:217], v161 offset:672
	s_waitcnt vmcnt(12)
	s_waitcnt lgkmcnt(2)
	v_cndmask_b32_e64 v218, v218, 0, s[8:9]
	v_cndmask_b32_e64 v219, v219, 0, s[8:9]
	v_cndmask_b32_e64 v220, v220, 0, s[8:9]
	v_cndmask_b32_e64 v221, v221, 0, s[8:9]
	v_cvt_pk_bf16_f32 v138, v138, v139
	v_cvt_pk_bf16_f32 v139, v140, v141
	v_cvt_pk_bf16_f32 v140, v142, v143
	v_cvt_pk_bf16_f32 v141, v144, v145
	v_cvt_pk_bf16_f32 v146, v146, v147
	v_cvt_pk_bf16_f32 v147, v148, v149
	v_cvt_pk_bf16_f32 v148, v150, v151
	v_cvt_pk_bf16_f32 v149, v152, v153
	v_mfma_f32_16x16x32_bf16 v[4:7], v[138:141], v[218:221], v[4:7]
	s_nop 0
	v_mfma_f32_16x16x32_bf16 v[0:3], v[146:149], v[218:221], v[0:3]
	global_load_dwordx4 v[138:141], v[224:225], off offset:1664
	global_load_dwordx4 v[142:145], v[224:225], off offset:1728
	global_load_dwordx4 v[146:149], v[222:223], off offset:1664
	global_load_dwordx4 v[150:153], v[222:223], off offset:1728
	ds_read_b64 v[218:219], v161 offset:704
	ds_read_b64 v[220:221], v161 offset:736
	s_waitcnt vmcnt(12)
	s_waitcnt lgkmcnt(2)
	v_cndmask_b32_e64 v214, v214, 0, s[8:9]
	v_cndmask_b32_e64 v215, v215, 0, s[8:9]
	v_cndmask_b32_e64 v216, v216, 0, s[8:9]
	v_cndmask_b32_e64 v217, v217, 0, s[8:9]
	v_cvt_pk_bf16_f32 v166, v166, v167
	v_cvt_pk_bf16_f32 v167, v168, v169
	v_cvt_pk_bf16_f32 v168, v170, v171
	v_cvt_pk_bf16_f32 v169, v172, v173
	v_cvt_pk_bf16_f32 v174, v174, v175
	v_cvt_pk_bf16_f32 v175, v176, v177
	v_cvt_pk_bf16_f32 v176, v178, v179
	v_cvt_pk_bf16_f32 v177, v180, v181
	v_mfma_f32_16x16x32_bf16 v[4:7], v[166:169], v[214:217], v[4:7]
	s_nop 0
	v_mfma_f32_16x16x32_bf16 v[0:3], v[174:177], v[214:217], v[0:3]
	global_load_dwordx4 v[166:169], v[224:225], off offset:1792
	global_load_dwordx4 v[170:173], v[224:225], off offset:1856
	global_load_dwordx4 v[174:177], v[222:223], off offset:1792
	global_load_dwordx4 v[178:181], v[222:223], off offset:1856
	ds_read_b64 v[214:215], v161 offset:768
	ds_read_b64 v[216:217], v161 offset:800
	s_waitcnt vmcnt(12)
	s_waitcnt lgkmcnt(2)
	v_cndmask_b32_e64 v218, v218, 0, s[8:9]
	v_cndmask_b32_e64 v219, v219, 0, s[8:9]
	v_cndmask_b32_e64 v220, v220, 0, s[8:9]
	v_cndmask_b32_e64 v221, v221, 0, s[8:9]
	v_cvt_pk_bf16_f32 v198, v198, v199
	v_cvt_pk_bf16_f32 v199, v200, v201
	v_cvt_pk_bf16_f32 v200, v202, v203
	v_cvt_pk_bf16_f32 v201, v204, v205
	v_cvt_pk_bf16_f32 v206, v206, v207
	v_cvt_pk_bf16_f32 v207, v208, v209
	v_cvt_pk_bf16_f32 v208, v210, v211
	v_cvt_pk_bf16_f32 v209, v212, v213
	v_mfma_f32_16x16x32_bf16 v[4:7], v[198:201], v[218:221], v[4:7]
	s_nop 0
	v_mfma_f32_16x16x32_bf16 v[0:3], v[206:209], v[218:221], v[0:3]
	global_load_dwordx4 v[198:201], v[224:225], off offset:1920
	global_load_dwordx4 v[202:205], v[224:225], off offset:1984
	global_load_dwordx4 v[206:209], v[222:223], off offset:1920
	global_load_dwordx4 v[210:213], v[222:223], off offset:1984
	ds_read_b64 v[218:219], v161 offset:832
	ds_read_b64 v[220:221], v161 offset:864
	s_waitcnt vmcnt(12)
	s_waitcnt lgkmcnt(2)
	v_cndmask_b32_e64 v214, v214, 0, s[8:9]
	v_cndmask_b32_e64 v215, v215, 0, s[8:9]
	v_cndmask_b32_e64 v216, v216, 0, s[8:9]
	v_cndmask_b32_e64 v217, v217, 0, s[8:9]
	v_cvt_pk_bf16_f32 v122, v122, v123
	v_cvt_pk_bf16_f32 v123, v124, v125
	v_cvt_pk_bf16_f32 v124, v126, v127
	v_cvt_pk_bf16_f32 v125, v128, v129
	v_cvt_pk_bf16_f32 v130, v130, v131
	v_cvt_pk_bf16_f32 v131, v132, v133
	v_cvt_pk_bf16_f32 v132, v134, v135
	v_cvt_pk_bf16_f32 v133, v136, v137
	v_mfma_f32_16x16x32_bf16 v[4:7], v[122:125], v[214:217], v[4:7]
	s_nop 0
	v_mfma_f32_16x16x32_bf16 v[0:3], v[130:133], v[214:217], v[0:3]
	ds_read_b64 v[214:215], v161 offset:896
	ds_read_b64 v[216:217], v161 offset:928
	s_waitcnt vmcnt(8)
	s_waitcnt lgkmcnt(2)
	v_cndmask_b32_e64 v218, v218, 0, s[8:9]
	v_cndmask_b32_e64 v219, v219, 0, s[8:9]
	v_cndmask_b32_e64 v220, v220, 0, s[8:9]
	v_cndmask_b32_e64 v221, v221, 0, s[8:9]
	v_cvt_pk_bf16_f32 v138, v138, v139
	v_cvt_pk_bf16_f32 v139, v140, v141
	v_cvt_pk_bf16_f32 v140, v142, v143
	v_cvt_pk_bf16_f32 v141, v144, v145
	v_cvt_pk_bf16_f32 v146, v146, v147
	v_cvt_pk_bf16_f32 v147, v148, v149
	v_cvt_pk_bf16_f32 v148, v150, v151
	v_cvt_pk_bf16_f32 v149, v152, v153
	v_mfma_f32_16x16x32_bf16 v[4:7], v[138:141], v[218:221], v[4:7]
	s_nop 0
	v_mfma_f32_16x16x32_bf16 v[0:3], v[146:149], v[218:221], v[0:3]
	ds_read_b64 v[218:219], v161 offset:960
	ds_read_b64 v[220:221], v161 offset:992
	s_waitcnt vmcnt(4)
	s_waitcnt lgkmcnt(2)
	v_cndmask_b32_e64 v214, v214, 0, s[8:9]
	v_cndmask_b32_e64 v215, v215, 0, s[8:9]
	v_cndmask_b32_e64 v216, v216, 0, s[8:9]
	v_cndmask_b32_e64 v217, v217, 0, s[8:9]
	v_cvt_pk_bf16_f32 v166, v166, v167
	v_cvt_pk_bf16_f32 v167, v168, v169
	v_cvt_pk_bf16_f32 v168, v170, v171
	v_cvt_pk_bf16_f32 v169, v172, v173
	v_cvt_pk_bf16_f32 v174, v174, v175
	v_cvt_pk_bf16_f32 v175, v176, v177
	v_cvt_pk_bf16_f32 v176, v178, v179
	v_cvt_pk_bf16_f32 v177, v180, v181
	v_mfma_f32_16x16x32_bf16 v[4:7], v[166:169], v[214:217], v[4:7]
	s_nop 0
	v_mfma_f32_16x16x32_bf16 v[0:3], v[174:177], v[214:217], v[0:3]
	s_waitcnt vmcnt(0)
	s_waitcnt lgkmcnt(0)
	v_cndmask_b32_e64 v218, v218, 0, s[8:9]
	v_cndmask_b32_e64 v219, v219, 0, s[8:9]
	v_cndmask_b32_e64 v220, v220, 0, s[8:9]
	v_cndmask_b32_e64 v221, v221, 0, s[8:9]
	v_cvt_pk_bf16_f32 v198, v198, v199
	v_cvt_pk_bf16_f32 v199, v200, v201
	v_cvt_pk_bf16_f32 v200, v202, v203
	v_cvt_pk_bf16_f32 v201, v204, v205
	v_cvt_pk_bf16_f32 v206, v206, v207
	v_cvt_pk_bf16_f32 v207, v208, v209
	v_cvt_pk_bf16_f32 v208, v210, v211
	v_cvt_pk_bf16_f32 v209, v212, v213
	v_mfma_f32_16x16x32_bf16 v[4:7], v[198:201], v[218:221], v[4:7]
	s_nop 0
	v_mfma_f32_16x16x32_bf16 v[0:3], v[206:209], v[218:221], v[0:3]
	s_nop 7
	s_branch .LBB0_883
